# attention loops: priority kept raised from loop top through PV (A, D) and QK..PV (C); MLA loop: 32-bit SGPR-base prefetch addressing instead of per-tile 64-bit selects
# speedup vs baseline: 1.0393x; 1.0101x over previous
.LBB0_64:
	s_mulk_i32 s38, 0xc0
	s_add_u32 s14, s3, s38
	s_addc_u32 s15, s16, 0
	s_ashr_i32 s13, s12, 31
	s_lshl_b64 s[10:11], s[12:13], 10
	s_add_u32 s38, s17, s10
	s_addc_u32 s39, s18, s11
	s_lshl_b32 s40, s34, 1
	s_add_u32 s38, s38, s40
	s_addc_u32 s39, s39, 0
	s_lshl_b64 s[12:13], s[12:13], 6
	s_add_u32 s40, s19, s12
	s_addc_u32 s41, s20, s13
	v_lshl_add_u64 v[2:3], s[40:41], 0, v[136:137]
	s_movk_i32 s76, 0xff80
	v_lshl_add_u64 v[2:3], v[130:131], 1, v[2:3]
	s_mov_b32 s77, -1
	v_lshl_add_u64 v[4:5], s[38:39], 0, v[134:135]
	v_lshl_add_u64 v[2:3], v[2:3], 0, s[76:77]
	v_lshl_add_u64 v[4:5], v[120:121], 1, v[4:5]
	v_cndmask_b32_e64 v3, v5, v3, s[0:1]
	v_cndmask_b32_e64 v2, v4, v2, s[0:1]
	global_load_dwordx4 v[4:7], v[2:3], off
	v_lshl_add_u64 v[2:3], s[40:41], 0, v[140:141]
	v_lshl_add_u64 v[2:3], v[132:133], 1, v[2:3]
	v_lshl_add_u64 v[8:9], s[38:39], 0, v[138:139]
	v_lshl_add_u64 v[2:3], v[2:3], 0, s[76:77]
	v_lshl_add_u64 v[8:9], v[122:123], 1, v[8:9]
	v_cndmask_b32_e64 v3, v9, v3, s[6:7]
	v_cndmask_b32_e64 v2, v8, v2, s[6:7]
	global_load_dwordx4 v[8:11], v[2:3], off
	v_lshl_add_u64 v[2:3], s[40:41], 0, v[148:149]
	v_lshl_add_u64 v[2:3], v[144:145], 1, v[2:3]
	v_lshl_add_u64 v[12:13], s[38:39], 0, v[142:143]
	v_lshl_add_u64 v[2:3], v[2:3], 0, s[76:77]
	v_lshl_add_u64 v[12:13], v[124:125], 1, v[12:13]
	v_mad_i64_i32 v[16:17], s[38:39], s36, v126, 0
	v_mad_i64_i32 v[18:19], s[38:39], s36, v128, 0
	v_cndmask_b32_e64 v3, v13, v3, s[4:5]
	v_cndmask_b32_e64 v2, v12, v2, s[4:5]
	v_mov_b32_e32 v169, v1
	s_lshl_b32 s38, s31, 4
	global_load_dwordx4 v[12:15], v[2:3], off
	v_lshl_add_u64 v[2:3], s[8:9], 0, v[168:169]
	s_and_b32 s37, s37, s38
	v_lshl_add_u64 v[16:17], v[16:17], 1, v[2:3]
	v_lshl_add_u64 v[2:3], v[18:19], 1, v[2:3]
	s_add_i32 s35, s35, s37
	global_load_dwordx4 v[16:19], v[16:17], off
	s_nop 0
	global_load_dwordx4 v[20:23], v[2:3], off
	v_add_u32_e32 v170, s35, v119
	v_mov_b64_e32 v[2:3], s[14:15]
	s_movk_i32 s14, 0x600
	v_mad_i64_i32 v[2:3], s[14:15], v170, s14, v[2:3]
	v_lshlrev_b32_e32 v24, 1, v118
	v_mov_b32_e32 v25, v1
	v_lshl_add_u64 v[2:3], v[2:3], 0, v[24:25]
	global_load_dwordx4 v[86:89], v[2:3], off
	global_load_dwordx4 v[82:85], v[2:3], off offset:32
	global_load_dwordx4 v[78:81], v[2:3], off offset:64
	global_load_dwordx4 v[74:77], v[2:3], off offset:96
	global_load_dwordx4 v[70:73], v[2:3], off offset:128
	global_load_dwordx4 v[66:69], v[2:3], off offset:160
	v_lshl_add_u64 v[24:25], s[8:9], 0, v[150:151]
	v_lshl_add_u64 v[24:25], v[24:25], 0, s[52:53]
	v_mad_i64_i32 v[172:173], s[8:9], v152, s36, v[24:25]
	v_mad_i64_i32 v[174:175], s[8:9], v154, s36, v[24:25]
	v_add_u32_e32 v3, v147, v189
	s_and_b32 s9, s30, 7
	v_add_u32_e32 v26, v190, v191
	v_add_u32_e32 v27, v192, v193
	v_add3_u32 v28, v194, v195, s59
	v_add3_u32 v29, v194, v196, s59
	s_lshl_b32 s9, s9, 7
	v_mov_b32_e32 v2, v1
	s_or_b32 s10, s10, s9
	s_mov_b32 s14, 1
	v_lshl_add_u64 v[176:177], v[156:157], 0, s[12:13]
	v_lshl_add_u64 v[178:179], v[160:161], 0, s[12:13]
	v_lshl_add_u64 v[180:181], v[164:165], 0, s[12:13]
	s_lshr_b32 s8, s36, 6
	v_lshl_add_u64 v[182:183], s[10:11], 0, v[158:159]
	v_lshl_add_u64 v[184:185], s[10:11], 0, v[162:163]
	v_lshl_add_u64 v[186:187], s[10:11], 0, v[166:167]
	v_cndmask_b32_e64 v180, v186, v180, s[0:1]
	v_cndmask_b32_e64 v178, v184, v178, s[6:7]
	v_cndmask_b32_e64 v176, v182, v176, s[4:5]
	v_mov_b32_e32 v182, 0x10000
	v_mov_b32_e32 v184, 0x1000
	v_cndmask_b32_e64 v181, v182, v184, s[0:1]
	v_cndmask_b32_e64 v179, v182, v184, s[6:7]
	v_cndmask_b32_e64 v177, v182, v184, s[4:5]
	v_ashrrev_i32_e32 v171, 31, v170
	v_mov_b32_e32 v127, 0
	v_mov_b32_e32 v188, 0xff800000
	s_waitcnt vmcnt(10)
	ds_write_b128 v3, v[4:7]
	s_waitcnt vmcnt(9)
	ds_write_b128 v26, v[8:11]
	s_waitcnt vmcnt(8)
	ds_write_b128 v27, v[12:15]
	s_waitcnt vmcnt(7)
	ds_write2_b64 v28, v[16:17], v[18:19] offset1:1
	s_waitcnt vmcnt(6)
	ds_write2_b64 v29, v[20:21], v[22:23] offset1:1
	v_mov_b32_e32 v16, v1
	v_mov_b32_e32 v17, v1
	v_mov_b32_e32 v3, v1
	v_mov_b32_e32 v4, v1
	v_mov_b32_e32 v5, v1
	v_mov_b32_e32 v6, v1
	v_mov_b32_e32 v7, v1
	v_mov_b32_e32 v8, v1
	v_mov_b32_e32 v9, v1
	v_mov_b32_e32 v10, v1
	v_mov_b32_e32 v11, v1
	v_mov_b32_e32 v12, v1
	v_mov_b32_e32 v13, v1
	v_mov_b32_e32 v14, v1
	v_mov_b32_e32 v15, v1
	v_mov_b64_e32 v[32:33], v[16:17]
	v_mov_b64_e32 v[30:31], v[14:15]
	v_mov_b64_e32 v[28:29], v[12:13]
	v_mov_b64_e32 v[26:27], v[10:11]
	v_mov_b64_e32 v[24:25], v[8:9]
	v_mov_b64_e32 v[22:23], v[6:7]
	v_mov_b64_e32 v[20:21], v[4:5]
	v_mov_b64_e32 v[18:19], v[2:3]
	s_waitcnt lgkmcnt(0)
	s_barrier
	s_branch .LBB0_66
.LBB0_65:
	v_fma_f32 v50, v50, s54, -v188
	v_fma_f32 v51, v51, s54, -v188
	v_exp_f32_e32 v50, v50
	v_exp_f32_e32 v51, v51
	v_fma_f32 v52, v52, s54, -v188
	v_fma_f32 v53, v53, s54, -v188
	v_add_f32_e32 v236, 0, v50
	v_add_f32_e32 v237, 0, v51
	v_exp_f32_e32 v52, v52
	v_exp_f32_e32 v53, v53
	v_fma_f32 v54, v54, s54, -v188
	v_fma_f32 v55, v55, s54, -v188
	v_add_f32_e32 v236, v52, v236
	v_add_f32_e32 v237, v53, v237
	v_exp_f32_e32 v54, v54
	v_exp_f32_e32 v55, v55
	v_fma_f32 v56, v56, s54, -v188
	v_fma_f32 v57, v57, s54, -v188
	v_add_f32_e32 v236, v54, v236
	v_add_f32_e32 v237, v55, v237
	v_exp_f32_e32 v56, v56
	v_exp_f32_e32 v57, v57
	v_fma_f32 v58, v58, s54, -v188
	v_fma_f32 v59, v59, s54, -v188
	v_add_f32_e32 v236, v56, v236
	v_add_f32_e32 v237, v57, v237
	v_exp_f32_e32 v58, v58
	v_exp_f32_e32 v59, v59
	v_fma_f32 v60, v60, s54, -v188
	v_fma_f32 v61, v61, s54, -v188
	v_add_f32_e32 v236, v58, v236
	v_add_f32_e32 v237, v59, v237
	v_exp_f32_e32 v60, v60
	v_exp_f32_e32 v61, v61
	v_fma_f32 v62, v62, s54, -v188
	v_fma_f32 v63, v63, s54, -v188
	v_add_f32_e32 v236, v60, v236
	v_add_f32_e32 v237, v61, v237
	v_exp_f32_e32 v62, v62
	v_exp_f32_e32 v63, v63
	v_fma_f32 v64, v64, s54, -v188
	v_fma_f32 v65, v65, s54, -v188
	v_add_f32_e32 v236, v62, v236
	v_add_f32_e32 v237, v63, v237
	v_exp_f32_e32 v64, v64
	v_exp_f32_e32 v65, v65
	v_fma_f32 v34, v34, s54, -v188
	v_fma_f32 v35, v35, s54, -v188
	v_add_f32_e32 v236, v64, v236
	v_add_f32_e32 v237, v65, v237
	v_exp_f32_e32 v202, v34
	v_exp_f32_e32 v203, v35
	v_fma_f32 v36, v36, s54, -v188
	v_fma_f32 v37, v37, s54, -v188
	v_add_f32_e32 v236, v202, v236
	v_add_f32_e32 v237, v203, v237
	v_exp_f32_e32 v204, v36
	v_exp_f32_e32 v205, v37
	v_fma_f32 v38, v38, s54, -v188
	v_fma_f32 v39, v39, s54, -v188
	v_add_f32_e32 v236, v204, v236
	v_add_f32_e32 v237, v205, v237
	v_exp_f32_e32 v218, v38
	v_exp_f32_e32 v219, v39
	v_fma_f32 v40, v40, s54, -v188
	v_fma_f32 v41, v41, s54, -v188
	v_add_f32_e32 v236, v218, v236
	v_add_f32_e32 v237, v219, v237
	v_exp_f32_e32 v220, v40
	v_exp_f32_e32 v221, v41
	v_fma_f32 v42, v42, s54, -v188
	v_fma_f32 v43, v43, s54, -v188
	v_add_f32_e32 v236, v220, v236
	v_add_f32_e32 v237, v221, v237
	v_exp_f32_e32 v200, v42
	v_exp_f32_e32 v201, v43
	v_fma_f32 v44, v44, s54, -v188
	v_fma_f32 v45, v45, s54, -v188
	v_add_f32_e32 v236, v200, v236
	v_add_f32_e32 v237, v201, v237
	v_exp_f32_e32 v222, v44
	v_exp_f32_e32 v223, v45
	v_fma_f32 v46, v46, s54, -v188
	v_fma_f32 v47, v47, s54, -v188
	v_add_f32_e32 v236, v222, v236
	v_add_f32_e32 v237, v223, v237
	v_exp_f32_e32 v232, v46
	v_exp_f32_e32 v233, v47
	v_fma_f32 v48, v48, s54, -v188
	v_fma_f32 v49, v49, s54, -v188
	v_add_f32_e32 v236, v232, v236
	v_add_f32_e32 v237, v233, v237
	v_exp_f32_e32 v234, v48
	v_exp_f32_e32 v235, v49
	v_add_f32_e32 v236, v234, v236
	v_add_f32_e32 v237, v235, v237
	s_nop 0
	v_add_f32_e32 v155, v236, v237
	ds_read2_b64 v[38:41], v153 offset0:132 offset1:134
	ds_read2_b64 v[42:45], v129 offset0:164 offset1:166
	v_cvt_pk_bf16_f32 v34, v50, v51
	v_cvt_pk_bf16_f32 v35, v52, v53
	v_cvt_pk_bf16_f32 v36, v54, v55
	v_cvt_pk_bf16_f32 v37, v56, v57
	s_waitcnt lgkmcnt(3)
	s_nop 0
	v_mfma_f32_32x32x16_bf16 v[18:33], v[110:113], v[34:37], v[18:33]
	s_waitcnt lgkmcnt(2)
	v_mfma_f32_32x32x16_bf16 v[2:17], v[114:117], v[34:37], v[2:17]
	ds_read2_b64 v[46:49], v153 offset0:136 offset1:138
	ds_read2_b64 v[50:53], v129 offset0:168 offset1:170
	v_cvt_pk_bf16_f32 v34, v58, v59
	v_cvt_pk_bf16_f32 v35, v60, v61
	v_cvt_pk_bf16_f32 v36, v62, v63
	v_cvt_pk_bf16_f32 v37, v64, v65
	s_waitcnt lgkmcnt(3)
	s_nop 0
	v_mfma_f32_32x32x16_bf16 v[18:33], v[38:41], v[34:37], v[18:33]
	s_waitcnt lgkmcnt(2)
	v_mfma_f32_32x32x16_bf16 v[2:17], v[42:45], v[34:37], v[2:17]
	ds_read2_b64 v[38:41], v153 offset0:140 offset1:142
	ds_read2_b64 v[42:45], v129 offset0:172 offset1:174
	v_cvt_pk_bf16_f32 v34, v202, v203
	v_cvt_pk_bf16_f32 v35, v204, v205
	v_cvt_pk_bf16_f32 v36, v218, v219
	v_cvt_pk_bf16_f32 v37, v220, v221
	s_waitcnt lgkmcnt(3)
	s_nop 0
	v_mfma_f32_32x32x16_bf16 v[18:33], v[46:49], v[34:37], v[18:33]
	s_waitcnt lgkmcnt(2)
	v_mfma_f32_32x32x16_bf16 v[2:17], v[50:53], v[34:37], v[2:17]
	v_cvt_pk_bf16_f32 v34, v200, v201
	v_cvt_pk_bf16_f32 v35, v222, v223
	v_cvt_pk_bf16_f32 v36, v232, v233
	v_cvt_pk_bf16_f32 v37, v234, v235
	s_waitcnt lgkmcnt(1)
	s_nop 0
	v_mfma_f32_32x32x16_bf16 v[18:33], v[38:41], v[34:37], v[18:33]
	s_waitcnt lgkmcnt(0)
	v_mfma_f32_32x32x16_bf16 v[2:17], v[42:45], v[34:37], v[2:17]
	v_add_f32_e32 v127, v127, v155
	s_setprio 0
	s_cmp_eq_u32 s9, 1
	s_cselect_b32 s9, 0x5600, 0
	v_add3_u32 v34, s9, v147, v189
	s_waitcnt vmcnt(4)
	ds_write_b128 v34, v[90:93]
	v_add3_u32 v34, s9, v190, v191
	s_waitcnt vmcnt(3)
	ds_write_b128 v34, v[94:97]
	v_add3_u32 v34, s9, v192, v193
	s_waitcnt vmcnt(2)
	ds_write_b128 v34, v[106:109]
	v_or_b32_e32 v34, s9, v194
	s_add_i32 s14, s14, 1
	v_add3_u32 v35, v34, v195, s59
	v_add3_u32 v34, v34, v196, s59
	v_lshl_add_u64 v[172:173], v[172:173], 0, s[52:53]
	v_lshl_add_u64 v[174:175], v[174:175], 0, s[52:53]
	v_add_u32_e32 v176, v176, v177
	v_add_u32_e32 v178, v178, v179
	v_add_u32_e32 v180, v180, v181
	s_cmp_eq_u32 s8, s14
	s_waitcnt vmcnt(1)
	ds_write2_b64 v35, v[102:103], v[104:105] offset1:1
	s_waitcnt vmcnt(0)
	ds_write2_b64 v34, v[98:99], v[100:101] offset1:1
	s_waitcnt lgkmcnt(0)
	s_barrier
	s_cbranch_scc1 .LBB0_49
.LBB0_66:
	s_setprio 1
	global_load_dwordx4 v[90:93], v180, s[62:63]
	global_load_dwordx4 v[94:97], v178, s[62:63]
	global_load_dwordx4 v[106:109], v176, s[62:63]
	global_load_dwordx4 v[102:105], v[172:173], off
	global_load_dwordx4 v[98:101], v[174:175], off
	s_and_b32 s9, 1, s14
	s_cselect_b32 s10, 0, 0x5600
	v_or_b32_e32 v34, s10, v197
	v_add_u32_e32 v129, v34, v198
	ds_read_b128 v[34:37], v129
	ds_read_b128 v[38:41], v129 offset:6656
	ds_read_b128 v[110:113], v129 offset:32
	ds_read_b128 v[114:117], v129 offset:6688
	s_waitcnt vmcnt(10) lgkmcnt(3)
	v_mfma_f32_32x32x16_bf16 v[50:65], v[34:37], v[86:89], 0
	s_waitcnt lgkmcnt(2)
	v_mfma_f32_32x32x16_bf16 v[34:49], v[38:41], v[86:89], 0
	ds_read_b128 v[200:203], v129 offset:64
	ds_read_b128 v[232:235], v129 offset:6720
	s_waitcnt vmcnt(9) lgkmcnt(3)
	v_mfma_f32_32x32x16_bf16 v[50:65], v[110:113], v[82:85], v[50:65]
	s_waitcnt lgkmcnt(2)
	v_mfma_f32_32x32x16_bf16 v[34:49], v[114:117], v[82:85], v[34:49]
	ds_read_b128 v[110:113], v129 offset:96
	ds_read_b128 v[114:117], v129 offset:6752
	s_waitcnt vmcnt(8) lgkmcnt(3)
	v_mfma_f32_32x32x16_bf16 v[50:65], v[200:203], v[78:81], v[50:65]
	s_waitcnt lgkmcnt(2)
	v_mfma_f32_32x32x16_bf16 v[34:49], v[232:235], v[78:81], v[34:49]
	ds_read_b128 v[200:203], v129 offset:128
	ds_read_b128 v[232:235], v129 offset:6784
	s_waitcnt vmcnt(7) lgkmcnt(3)
	v_mfma_f32_32x32x16_bf16 v[50:65], v[110:113], v[74:77], v[50:65]
	s_waitcnt lgkmcnt(2)
	v_mfma_f32_32x32x16_bf16 v[34:49], v[114:117], v[74:77], v[34:49]
	ds_read_b128 v[110:113], v129 offset:160
	ds_read_b128 v[114:117], v129 offset:6816
	s_waitcnt vmcnt(6) lgkmcnt(3)
	v_mfma_f32_32x32x16_bf16 v[50:65], v[200:203], v[70:73], v[50:65]
	s_waitcnt lgkmcnt(2)
	v_mfma_f32_32x32x16_bf16 v[34:49], v[232:235], v[70:73], v[34:49]
	s_waitcnt vmcnt(5) lgkmcnt(1)
	v_mfma_f32_32x32x16_bf16 v[50:65], v[110:113], v[66:69], v[50:65]
	s_waitcnt lgkmcnt(0)
	v_mfma_f32_32x32x16_bf16 v[34:49], v[114:117], v[66:69], v[34:49]
	v_or_b32_e32 v110, s10, v118
	v_add_u32_e32 v114, v110, v199
	v_add_u32_e32 v153, 0x3000, v114
	v_add_u32_e32 v129, 0x4000, v114
	ds_read2_b64 v[110:113], v153 offset0:128 offset1:130
	ds_read2_b64 v[114:117], v129 offset0:160 offset1:162
	s_nop 2
	v_max3_f32 v155, v50, s55, v51
	v_max3_f32 v155, v155, v52, v53
	v_max3_f32 v155, v155, v54, v55
	v_max3_f32 v155, v155, v56, v57
	v_max3_f32 v155, v155, v58, v59
	v_max3_f32 v155, v155, v60, v61
	v_max3_f32 v155, v155, v62, v63
	v_max3_f32 v155, v155, v64, v65
	v_max3_f32 v155, v155, v34, v35
	v_max3_f32 v155, v155, v36, v37
	v_max3_f32 v155, v155, v38, v39
	v_max3_f32 v155, v155, v40, v41
	v_max3_f32 v155, v155, v42, v43
	v_max3_f32 v155, v155, v44, v45
	v_max3_f32 v155, v155, v46, v47
	v_max3_f32 v155, v155, v48, v49
	v_mov_b32_e32 v169, v155
	s_nop 1
	v_permlane32_swap_b32_e32 v155, v169
	v_max_f32_e32 v169, v169, v169
	v_max_f32_e32 v155, v155, v155
	v_max_f32_e32 v155, v155, v169
	v_mul_f32_e32 v155, 0x3e16c740, v155
	v_add_f32_e32 v169, 0x41000000, v188
	v_cmp_gt_f32_e32 vcc, v155, v169
	s_cbranch_vccz .LBB0_65
	v_max_f32_e32 v155, v155, v155
	v_max_f32_e32 v169, v188, v188
	v_max_f32_e32 v155, v169, v155
	v_sub_f32_e32 v169, v188, v155
	v_exp_f32_e32 v188, v169
	s_nop 0
	v_pk_mul_f32 v[32:33], v[32:33], v[188:189] op_sel_hi:[1,0]
	v_pk_mul_f32 v[30:31], v[30:31], v[188:189] op_sel_hi:[1,0]
	v_pk_mul_f32 v[28:29], v[28:29], v[188:189] op_sel_hi:[1,0]
	v_pk_mul_f32 v[26:27], v[26:27], v[188:189] op_sel_hi:[1,0]
	v_pk_mul_f32 v[24:25], v[24:25], v[188:189] op_sel_hi:[1,0]
	v_pk_mul_f32 v[22:23], v[22:23], v[188:189] op_sel_hi:[1,0]
	v_pk_mul_f32 v[20:21], v[20:21], v[188:189] op_sel_hi:[1,0]
	v_pk_mul_f32 v[18:19], v[18:19], v[188:189] op_sel_hi:[1,0]
	v_pk_mul_f32 v[16:17], v[16:17], v[188:189] op_sel_hi:[1,0]
	v_pk_mul_f32 v[14:15], v[14:15], v[188:189] op_sel_hi:[1,0]
	v_pk_mul_f32 v[12:13], v[12:13], v[188:189] op_sel_hi:[1,0]
	v_pk_mul_f32 v[10:11], v[10:11], v[188:189] op_sel_hi:[1,0]
	v_pk_mul_f32 v[8:9], v[8:9], v[188:189] op_sel_hi:[1,0]
	v_pk_mul_f32 v[6:7], v[6:7], v[188:189] op_sel_hi:[1,0]
	v_pk_mul_f32 v[4:5], v[4:5], v[188:189] op_sel_hi:[1,0]
	v_pk_mul_f32 v[2:3], v[2:3], v[188:189] op_sel_hi:[1,0]
	v_mul_f32_e32 v127, v127, v188
	v_mov_b32_e32 v188, v155
	s_branch .LBB0_65

.LBB0_224:
	s_and_saveexec_b64 s[46:47], s[42:43]
	s_cbranch_execz .LBB0_294
	s_bitcmp1_b32 s70, 0
	s_cselect_b32 s42, 0x4600, 0
	v_or_b32_e32 v0, s42, v204
	v_add_u32_e32 v0, v0, v205
	ds_read_b128 v[2:5], v0
	ds_read_b128 v[6:9], v0 offset:4608
	s_setprio 1
	ds_read_b128 v[10:13], v0 offset:32
	ds_read_b128 v[176:179], v0 offset:4640
	s_waitcnt vmcnt(3) lgkmcnt(3)
	v_mfma_f32_32x32x16_bf16 v[64:79], v[2:5], v[80:83], 0
	s_waitcnt lgkmcnt(2)
	v_mfma_f32_32x32x16_bf16 v[48:63], v[6:9], v[80:83], 0
	ds_read_b128 v[2:5], v0 offset:64
	ds_read_b128 v[6:9], v0 offset:4672
	s_waitcnt vmcnt(2) lgkmcnt(3)
	v_mfma_f32_32x32x16_bf16 v[64:79], v[10:13], v[84:87], v[64:79]
	s_waitcnt lgkmcnt(2)
	v_mfma_f32_32x32x16_bf16 v[48:63], v[176:179], v[84:87], v[48:63]
	ds_read_b128 v[10:13], v0 offset:96
	ds_read_b128 v[176:179], v0 offset:4704
	s_waitcnt vmcnt(1) lgkmcnt(3)
	v_mfma_f32_32x32x16_bf16 v[64:79], v[2:5], v[88:91], v[64:79]
	s_waitcnt lgkmcnt(2)
	v_mfma_f32_32x32x16_bf16 v[48:63], v[6:9], v[88:91], v[48:63]
	s_waitcnt vmcnt(0) lgkmcnt(1)
	v_mfma_f32_32x32x16_bf16 v[64:79], v[10:13], v[92:95], v[64:79]
	s_waitcnt lgkmcnt(0)
	v_mfma_f32_32x32x16_bf16 v[48:63], v[176:179], v[92:95], v[48:63]
	v_or_b32_e32 v0, s42, v112
	v_add_u32_e32 v0, v0, v232
	v_add_u32_e32 v155, 0x2000, v0
	v_add_u32_e32 v0, 0x3000, v0
	ds_read2_b64 v[2:5], v155 offset0:128 offset1:130
	ds_read2_b64 v[6:9], v0 offset0:160 offset1:162
	s_mov_b64 s[42:43], -1
	s_and_b64 vcc, exec, s[64:65]
	s_nop 2
	v_mov_b32_e32 v201, v63
	v_mov_b32_e32 v200, v62
	v_mov_b32_e32 v199, v61
	v_mov_b32_e32 v198, v60
	v_mov_b32_e32 v197, v59
	v_mov_b32_e32 v196, v58
	v_mov_b32_e32 v195, v57
	v_mov_b32_e32 v194, v56
	v_mov_b32_e32 v193, v55
	v_mov_b32_e32 v192, v54
	v_mov_b32_e32 v191, v53
	v_mov_b32_e32 v190, v52
	v_mov_b32_e32 v189, v51
	v_mov_b32_e32 v188, v50
	v_mov_b32_e32 v187, v49
	v_mov_b32_e32 v186, v48
	v_mov_b32_e32 v185, v79
	v_mov_b32_e32 v184, v78
	v_mov_b32_e32 v183, v77
	v_mov_b32_e32 v182, v76
	v_mov_b32_e32 v181, v75
	v_mov_b32_e32 v180, v74
	v_mov_b32_e32 v179, v73
	v_mov_b32_e32 v178, v72
	v_mov_b32_e32 v177, v71
	v_mov_b32_e32 v176, v70
	v_mov_b32_e32 v15, v69
	v_mov_b32_e32 v14, v68
	v_mov_b32_e32 v13, v67
	v_mov_b32_e32 v12, v66
	v_mov_b32_e32 v11, v65
	v_mov_b32_e32 v10, v64
	s_cbranch_vccz .LBB0_296
	s_add_i32 s42, s67, s70
	v_cmp_ge_i32_e32 vcc, s42, v145
	v_cmp_lt_i32_e64 s[42:43], s42, v149
	v_readlane_b32 s64, v254, 24
	s_and_b64 s[42:43], vcc, s[42:43]
	v_readlane_b32 s65, v254, 25
	s_and_b64 s[74:75], s[42:43], s[64:65]
	v_mov_b32_e32 v11, 0xff800000
	v_mov_b32_e32 v10, 0xff800000
	s_and_saveexec_b64 s[64:65], s[74:75]
	s_cbranch_execz .LBB0_228
	ds_read_b32 v10, v153
	s_waitcnt lgkmcnt(0)
	v_fmac_f32_e32 v10, 0x3e38aa3b, v64

.LBB0_293:
	v_mov_b32_e32 v48, 0x3e38aa3b
	v_cndmask_b32_e64 v48, 1.0, v48, s[48:49]
	v_pk_fma_f32 v[10:11], v[48:49], v[10:11], v[174:175] op_sel_hi:[0,1,0] neg_lo:[0,0,1] neg_hi:[0,0,1]
	v_exp_f32_e32 v10, v10
	v_exp_f32_e32 v11, v11
	v_pk_fma_f32 v[12:13], v[48:49], v[12:13], v[174:175] op_sel_hi:[0,1,0] neg_lo:[0,0,1] neg_hi:[0,0,1]
	v_exp_f32_e32 v12, v12
	v_exp_f32_e32 v13, v13
	v_pk_fma_f32 v[14:15], v[48:49], v[14:15], v[174:175] op_sel_hi:[0,1,0] neg_lo:[0,0,1] neg_hi:[0,0,1]
	v_exp_f32_e32 v14, v14
	v_exp_f32_e32 v15, v15
	v_pk_fma_f32 v[50:51], v[48:49], v[176:177], v[174:175] op_sel_hi:[0,1,0] neg_lo:[0,0,1] neg_hi:[0,0,1]
	v_exp_f32_e32 v50, v50
	v_exp_f32_e32 v51, v51
	v_pk_fma_f32 v[54:55], v[48:49], v[178:179], v[174:175] op_sel_hi:[0,1,0] neg_lo:[0,0,1] neg_hi:[0,0,1]
	v_pk_add_f32 v[52:53], v[10:11], 0 op_sel_hi:[1,0]
	v_exp_f32_e32 v56, v54
	v_exp_f32_e32 v57, v55
	v_pk_fma_f32 v[54:55], v[48:49], v[180:181], v[174:175] op_sel_hi:[0,1,0] neg_lo:[0,0,1] neg_hi:[0,0,1]
	v_pk_add_f32 v[52:53], v[12:13], v[52:53]
	v_exp_f32_e32 v58, v54
	v_exp_f32_e32 v59, v55
	v_pk_fma_f32 v[54:55], v[48:49], v[182:183], v[174:175] op_sel_hi:[0,1,0] neg_lo:[0,0,1] neg_hi:[0,0,1]
	v_pk_add_f32 v[52:53], v[14:15], v[52:53]
	v_exp_f32_e32 v60, v54
	v_exp_f32_e32 v61, v55
	v_pk_fma_f32 v[54:55], v[48:49], v[184:185], v[174:175] op_sel_hi:[0,1,0] neg_lo:[0,0,1] neg_hi:[0,0,1]
	v_pk_add_f32 v[52:53], v[50:51], v[52:53]
	v_exp_f32_e32 v62, v54
	v_exp_f32_e32 v63, v55
	v_pk_fma_f32 v[54:55], v[48:49], v[186:187], v[174:175] op_sel_hi:[0,1,0] neg_lo:[0,0,1] neg_hi:[0,0,1]
	v_pk_add_f32 v[52:53], v[56:57], v[52:53]
	v_exp_f32_e32 v64, v54
	v_exp_f32_e32 v65, v55
	v_pk_fma_f32 v[54:55], v[48:49], v[188:189], v[174:175] op_sel_hi:[0,1,0] neg_lo:[0,0,1] neg_hi:[0,0,1]
	v_pk_add_f32 v[52:53], v[58:59], v[52:53]
	v_exp_f32_e32 v66, v54
	v_exp_f32_e32 v67, v55
	v_pk_fma_f32 v[54:55], v[48:49], v[190:191], v[174:175] op_sel_hi:[0,1,0] neg_lo:[0,0,1] neg_hi:[0,0,1]
	v_pk_add_f32 v[52:53], v[60:61], v[52:53]
	v_exp_f32_e32 v68, v54
	v_exp_f32_e32 v69, v55
	v_pk_fma_f32 v[54:55], v[48:49], v[192:193], v[174:175] op_sel_hi:[0,1,0] neg_lo:[0,0,1] neg_hi:[0,0,1]
	v_pk_add_f32 v[52:53], v[62:63], v[52:53]
	v_exp_f32_e32 v70, v54
	v_exp_f32_e32 v71, v55
	v_pk_fma_f32 v[54:55], v[48:49], v[194:195], v[174:175] op_sel_hi:[0,1,0] neg_lo:[0,0,1] neg_hi:[0,0,1]
	v_pk_add_f32 v[52:53], v[64:65], v[52:53]
	v_exp_f32_e32 v72, v54
	v_exp_f32_e32 v73, v55
	v_pk_fma_f32 v[54:55], v[48:49], v[196:197], v[174:175] op_sel_hi:[0,1,0] neg_lo:[0,0,1] neg_hi:[0,0,1]
	v_pk_add_f32 v[52:53], v[66:67], v[52:53]
	v_exp_f32_e32 v74, v54
	v_exp_f32_e32 v75, v55
	v_pk_fma_f32 v[54:55], v[48:49], v[198:199], v[174:175] op_sel_hi:[0,1,0] neg_lo:[0,0,1] neg_hi:[0,0,1]
	v_pk_add_f32 v[52:53], v[68:69], v[52:53]
	v_exp_f32_e32 v76, v54
	v_exp_f32_e32 v77, v55
	v_pk_fma_f32 v[48:49], v[48:49], v[200:201], v[174:175] op_sel_hi:[0,1,0] neg_lo:[0,0,1] neg_hi:[0,0,1]
	v_pk_add_f32 v[52:53], v[70:71], v[52:53]
	v_exp_f32_e32 v78, v48
	v_exp_f32_e32 v79, v49
	v_pk_add_f32 v[48:49], v[72:73], v[52:53]
	s_nop 0
	v_pk_add_f32 v[48:49], v[74:75], v[48:49]
	s_nop 0
	v_pk_add_f32 v[48:49], v[76:77], v[48:49]
	s_nop 0
	v_pk_add_f32 v[48:49], v[78:79], v[48:49]
	s_nop 0
	v_add_f32_e32 v157, v48, v49
	v_cvt_pk_bf16_f32 v10, v10, v11
	v_cvt_pk_bf16_f32 v11, v12, v13
	v_cvt_pk_bf16_f32 v13, v50, v51
	ds_read2_b64 v[48:51], v155 offset0:132 offset1:134
	ds_read2_b64 v[52:55], v0 offset0:164 offset1:166
	v_cvt_pk_bf16_f32 v12, v14, v15
	s_waitcnt lgkmcnt(3)
	s_nop 0
	v_mfma_f32_32x32x16_bf16 v[32:47], v[2:5], v[10:13], v[32:47]
	s_waitcnt lgkmcnt(2)
	v_mfma_f32_32x32x16_bf16 v[16:31], v[6:9], v[10:13], v[16:31]
	ds_read2_b64 v[6:9], v155 offset0:136 offset1:138
	ds_read2_b64 v[10:13], v0 offset0:168 offset1:170
	v_cvt_pk_bf16_f32 v2, v56, v57
	v_cvt_pk_bf16_f32 v3, v58, v59
	v_cvt_pk_bf16_f32 v4, v60, v61
	v_cvt_pk_bf16_f32 v5, v62, v63
	s_waitcnt lgkmcnt(3)
	s_nop 0
	v_mfma_f32_32x32x16_bf16 v[32:47], v[48:51], v[2:5], v[32:47]
	s_waitcnt lgkmcnt(2)
	v_mfma_f32_32x32x16_bf16 v[16:31], v[52:55], v[2:5], v[16:31]
	ds_read2_b64 v[48:51], v155 offset0:140 offset1:142
	ds_read2_b64 v[52:55], v0 offset0:172 offset1:174
	v_cvt_pk_bf16_f32 v2, v64, v65
	v_cvt_pk_bf16_f32 v3, v66, v67
	v_cvt_pk_bf16_f32 v4, v68, v69
	v_cvt_pk_bf16_f32 v5, v70, v71
	s_waitcnt lgkmcnt(3)
	s_nop 0
	v_mfma_f32_32x32x16_bf16 v[32:47], v[6:9], v[2:5], v[32:47]
	s_waitcnt lgkmcnt(2)
	v_mfma_f32_32x32x16_bf16 v[16:31], v[10:13], v[2:5], v[16:31]
	v_cvt_pk_bf16_f32 v2, v72, v73
	v_cvt_pk_bf16_f32 v3, v74, v75
	v_cvt_pk_bf16_f32 v4, v76, v77
	v_cvt_pk_bf16_f32 v5, v78, v79
	s_waitcnt lgkmcnt(1)
	s_nop 0
	v_mfma_f32_32x32x16_bf16 v[32:47], v[48:51], v[2:5], v[32:47]
	s_waitcnt lgkmcnt(0)
	v_mfma_f32_32x32x16_bf16 v[16:31], v[52:55], v[2:5], v[16:31]
	v_add_f32_e32 v151, v151, v157
	s_setprio 0

.LBB0_866:
	v_fma_f32 v64, v64, s58, -v160
	v_fma_f32 v65, v65, s58, -v160
	v_exp_f32_e32 v64, v64
	v_exp_f32_e32 v65, v65
	v_fma_f32 v66, v66, s58, -v160
	v_fma_f32 v67, v67, s58, -v160
	v_add_f32_e32 v222, 0, v64
	v_add_f32_e32 v223, 0, v65
	v_exp_f32_e32 v66, v66
	v_exp_f32_e32 v67, v67
	v_fma_f32 v68, v68, s58, -v160
	v_fma_f32 v69, v69, s58, -v160
	v_add_f32_e32 v222, v66, v222
	v_add_f32_e32 v223, v67, v223
	v_exp_f32_e32 v68, v68
	v_exp_f32_e32 v69, v69
	v_fma_f32 v70, v70, s58, -v160
	v_fma_f32 v71, v71, s58, -v160
	v_add_f32_e32 v222, v68, v222
	v_add_f32_e32 v223, v69, v223
	v_exp_f32_e32 v70, v70
	v_exp_f32_e32 v71, v71
	v_fma_f32 v72, v72, s58, -v160
	v_fma_f32 v73, v73, s58, -v160
	v_add_f32_e32 v222, v70, v222
	v_add_f32_e32 v223, v71, v223
	v_exp_f32_e32 v72, v72
	v_exp_f32_e32 v73, v73
	v_fma_f32 v74, v74, s58, -v160
	v_fma_f32 v75, v75, s58, -v160
	v_add_f32_e32 v222, v72, v222
	v_add_f32_e32 v223, v73, v223
	v_exp_f32_e32 v74, v74
	v_exp_f32_e32 v75, v75
	v_fma_f32 v76, v76, s58, -v160
	v_fma_f32 v77, v77, s58, -v160
	v_add_f32_e32 v222, v74, v222
	v_add_f32_e32 v223, v75, v223
	v_exp_f32_e32 v76, v76
	v_exp_f32_e32 v77, v77
	v_fma_f32 v78, v78, s58, -v160
	v_fma_f32 v79, v79, s58, -v160
	v_add_f32_e32 v222, v76, v222
	v_add_f32_e32 v223, v77, v223
	v_exp_f32_e32 v78, v78
	v_exp_f32_e32 v79, v79
	v_fma_f32 v48, v48, s58, -v160
	v_fma_f32 v49, v49, s58, -v160
	v_add_f32_e32 v222, v78, v222
	v_add_f32_e32 v223, v79, v223
	v_exp_f32_e32 v164, v48
	v_exp_f32_e32 v165, v49
	v_fma_f32 v50, v50, s58, -v160
	v_fma_f32 v51, v51, s58, -v160
	v_add_f32_e32 v222, v164, v222
	v_add_f32_e32 v223, v165, v223
	v_exp_f32_e32 v166, v50
	v_exp_f32_e32 v167, v51
	v_fma_f32 v52, v52, s58, -v160
	v_fma_f32 v53, v53, s58, -v160
	v_add_f32_e32 v222, v166, v222
	v_add_f32_e32 v223, v167, v223
	v_exp_f32_e32 v168, v52
	v_exp_f32_e32 v169, v53
	v_fma_f32 v54, v54, s58, -v160
	v_fma_f32 v55, v55, s58, -v160
	v_add_f32_e32 v222, v168, v222
	v_add_f32_e32 v223, v169, v223
	v_exp_f32_e32 v170, v54
	v_exp_f32_e32 v171, v55
	v_fma_f32 v56, v56, s58, -v160
	v_fma_f32 v57, v57, s58, -v160
	v_add_f32_e32 v222, v170, v222
	v_add_f32_e32 v223, v171, v223
	v_exp_f32_e32 v162, v56
	v_exp_f32_e32 v163, v57
	v_fma_f32 v58, v58, s58, -v160
	v_fma_f32 v59, v59, s58, -v160
	v_add_f32_e32 v222, v162, v222
	v_add_f32_e32 v223, v163, v223
	v_exp_f32_e32 v172, v58
	v_exp_f32_e32 v173, v59
	v_fma_f32 v60, v60, s58, -v160
	v_fma_f32 v61, v61, s58, -v160
	v_add_f32_e32 v222, v172, v222
	v_add_f32_e32 v223, v173, v223
	v_exp_f32_e32 v174, v60
	v_exp_f32_e32 v175, v61
	v_fma_f32 v62, v62, s58, -v160
	v_fma_f32 v63, v63, s58, -v160
	v_add_f32_e32 v222, v174, v222
	v_add_f32_e32 v223, v175, v223
	v_exp_f32_e32 v176, v62
	v_exp_f32_e32 v177, v63
	s_add_i32 s7, s7, 1
	v_add_f32_e32 v222, v176, v222
	v_add_f32_e32 v223, v177, v223
	s_nop 0
	v_add_f32_e32 v15, v222, v223
	ds_read2_b64 v[52:55], v14 offset0:132 offset1:134
	ds_read2_b64 v[56:59], v0 offset0:164 offset1:166
	v_cvt_pk_bf16_f32 v48, v64, v65
	v_cvt_pk_bf16_f32 v49, v66, v67
	v_cvt_pk_bf16_f32 v50, v68, v69
	v_cvt_pk_bf16_f32 v51, v70, v71
	s_waitcnt lgkmcnt(3)
	s_nop 0
	v_mfma_f32_32x32x16_bf16 v[32:47], v[100:103], v[48:51], v[32:47]
	s_waitcnt lgkmcnt(2)
	v_mfma_f32_32x32x16_bf16 v[16:31], v[104:107], v[48:51], v[16:31]
	ds_read2_b64 v[60:63], v14 offset0:136 offset1:138
	ds_read2_b64 v[64:67], v0 offset0:168 offset1:170
	v_cvt_pk_bf16_f32 v48, v72, v73
	v_cvt_pk_bf16_f32 v49, v74, v75
	v_cvt_pk_bf16_f32 v50, v76, v77
	v_cvt_pk_bf16_f32 v51, v78, v79
	s_waitcnt lgkmcnt(3)
	s_nop 0
	v_mfma_f32_32x32x16_bf16 v[32:47], v[52:55], v[48:51], v[32:47]
	s_waitcnt lgkmcnt(2)
	v_mfma_f32_32x32x16_bf16 v[16:31], v[56:59], v[48:51], v[16:31]
	ds_read2_b64 v[52:55], v14 offset0:140 offset1:142
	ds_read2_b64 v[56:59], v0 offset0:172 offset1:174
	v_cvt_pk_bf16_f32 v48, v164, v165
	v_cvt_pk_bf16_f32 v49, v166, v167
	v_cvt_pk_bf16_f32 v50, v168, v169
	v_cvt_pk_bf16_f32 v51, v170, v171
	s_waitcnt lgkmcnt(3)
	s_nop 0
	v_mfma_f32_32x32x16_bf16 v[32:47], v[60:63], v[48:51], v[32:47]
	s_waitcnt lgkmcnt(2)
	v_mfma_f32_32x32x16_bf16 v[16:31], v[64:67], v[48:51], v[16:31]
	v_cvt_pk_bf16_f32 v48, v162, v163
	v_cvt_pk_bf16_f32 v49, v172, v173
	v_cvt_pk_bf16_f32 v50, v174, v175
	v_cvt_pk_bf16_f32 v51, v176, v177
	s_waitcnt lgkmcnt(1)
	s_nop 0
	v_mfma_f32_32x32x16_bf16 v[32:47], v[52:55], v[48:51], v[32:47]
	s_waitcnt lgkmcnt(0)
	v_mfma_f32_32x32x16_bf16 v[16:31], v[56:59], v[48:51], v[16:31]
	v_add_f32_e32 v141, v141, v15
	s_setprio 0
	s_bitcmp1_b32 s7, 0
	s_cselect_b32 s0, 0x4600, 0
	v_add3_u32 v0, s0, v194, v195
	s_waitcnt vmcnt(3)
	ds_write_b128 v0, v[96:99]
	v_add3_u32 v0, s0, v196, v197
	s_waitcnt vmcnt(2)
	ds_write_b128 v0, v[10:13]
	v_or_b32_e32 v0, s0, v198
	v_add3_u32 v10, v0, v199, s33
	v_add3_u32 v0, v0, v200, s33
	v_lshl_add_u64 v[156:157], v[156:157], 0, s[52:53]
	v_lshl_add_u64 v[158:159], v[158:159], 0, s[52:53]
	v_lshl_add_u64 v[152:153], v[152:153], 0, s[60:61]
	s_cmp_eq_u32 s10, s7
	v_lshl_add_u64 v[154:155], v[154:155], 0, s[60:61]
	s_waitcnt vmcnt(1)
	ds_write2_b64 v10, v[2:3], v[4:5] offset1:1
	s_waitcnt vmcnt(0)
	ds_write2_b64 v0, v[6:7], v[8:9] offset1:1
	s_waitcnt lgkmcnt(0)
	s_barrier
	s_cbranch_scc1 .LBB0_788
.LBB0_867:
	s_setprio 1
	v_lshl_add_u64 v[2:3], v[156:157], 0, v[130:131]
	v_lshl_add_u64 v[6:7], v[158:159], 0, v[130:131]
	global_load_dwordx4 v[96:99], v[154:155], off
	global_load_dwordx4 v[10:13], v[152:153], off
	s_nop 0
	global_load_dwordx4 v[2:5], v[2:3], off
	s_nop 0
	global_load_dwordx4 v[6:9], v[6:7], off
	s_bitcmp1_b32 s7, 0
	s_cselect_b32 s0, 0x4600, 0
	v_or_b32_e32 v0, s0, v184
	v_add_u32_e32 v0, v0, v201
	ds_read_b128 v[48:51], v0
	ds_read_b128 v[52:55], v0 offset:4608
	ds_read_b128 v[100:103], v0 offset:32
	ds_read_b128 v[104:107], v0 offset:4640
	s_waitcnt vmcnt(7) lgkmcnt(3)
	v_mfma_f32_32x32x16_bf16 v[64:79], v[48:51], v[92:95], 0
	s_waitcnt lgkmcnt(2)
	v_mfma_f32_32x32x16_bf16 v[48:63], v[52:55], v[92:95], 0
	ds_read_b128 v[162:165], v0 offset:64
	ds_read_b128 v[166:169], v0 offset:4672
	s_waitcnt vmcnt(6) lgkmcnt(3)
	v_mfma_f32_32x32x16_bf16 v[64:79], v[100:103], v[88:91], v[64:79]
	s_waitcnt lgkmcnt(2)
	v_mfma_f32_32x32x16_bf16 v[48:63], v[104:107], v[88:91], v[48:63]
	ds_read_b128 v[100:103], v0 offset:96
	ds_read_b128 v[104:107], v0 offset:4704
	s_waitcnt vmcnt(5) lgkmcnt(3)
	v_mfma_f32_32x32x16_bf16 v[64:79], v[162:165], v[84:87], v[64:79]
	s_waitcnt lgkmcnt(2)
	v_mfma_f32_32x32x16_bf16 v[48:63], v[166:169], v[84:87], v[48:63]
	s_waitcnt vmcnt(4) lgkmcnt(1)
	v_mfma_f32_32x32x16_bf16 v[64:79], v[100:103], v[80:83], v[64:79]
	s_waitcnt lgkmcnt(0)
	v_mfma_f32_32x32x16_bf16 v[48:63], v[104:107], v[80:83], v[48:63]
	v_or_b32_e32 v0, s0, v116
	v_add_u32_e32 v0, v0, v202
	v_add_u32_e32 v14, 0x2000, v0
	v_add_u32_e32 v0, 0x3000, v0
	ds_read2_b64 v[100:103], v14 offset0:128 offset1:130
	ds_read2_b64 v[104:107], v0 offset0:160 offset1:162
	s_nop 2
	v_max3_f32 v15, v64, s55, v65
	v_max3_f32 v15, v15, v66, v67
	v_max3_f32 v15, v15, v68, v69
	v_max3_f32 v15, v15, v70, v71
	v_max3_f32 v15, v15, v72, v73
	v_max3_f32 v15, v15, v74, v75
	v_max3_f32 v15, v15, v76, v77
	v_max3_f32 v15, v15, v78, v79
	v_max3_f32 v15, v15, v48, v49
	v_max3_f32 v15, v15, v50, v51
	v_max3_f32 v15, v15, v52, v53
	v_max3_f32 v15, v15, v54, v55
	v_max3_f32 v15, v15, v56, v57
	v_max3_f32 v15, v15, v58, v59
	v_max3_f32 v15, v15, v60, v61
	v_max3_f32 v15, v15, v62, v63
	v_mov_b32_e32 v143, v15
	s_nop 1
	v_permlane32_swap_b32_e32 v15, v143
	v_max_f32_e32 v143, v143, v143
	v_max_f32_e32 v15, v15, v15
	v_max_f32_e32 v15, v15, v143
	v_mul_f32_e32 v15, 0x3e38aa3b, v15
	v_add_f32_e32 v143, 0x41000000, v160
	v_cmp_gt_f32_e32 vcc, v15, v143
	s_cbranch_vccz .LBB0_866
	v_max_f32_e32 v15, v15, v15
	v_max_f32_e32 v143, v160, v160
	v_max_f32_e32 v15, v143, v15
	v_sub_f32_e32 v143, v160, v15
	v_exp_f32_e32 v160, v143
	s_nop 0
	v_pk_mul_f32 v[46:47], v[46:47], v[160:161] op_sel_hi:[1,0]
	v_pk_mul_f32 v[44:45], v[44:45], v[160:161] op_sel_hi:[1,0]
	v_pk_mul_f32 v[42:43], v[42:43], v[160:161] op_sel_hi:[1,0]
	v_pk_mul_f32 v[40:41], v[40:41], v[160:161] op_sel_hi:[1,0]
	v_pk_mul_f32 v[38:39], v[38:39], v[160:161] op_sel_hi:[1,0]
	v_pk_mul_f32 v[36:37], v[36:37], v[160:161] op_sel_hi:[1,0]
	v_pk_mul_f32 v[34:35], v[34:35], v[160:161] op_sel_hi:[1,0]
	v_pk_mul_f32 v[32:33], v[32:33], v[160:161] op_sel_hi:[1,0]
	v_pk_mul_f32 v[30:31], v[30:31], v[160:161] op_sel_hi:[1,0]
	v_pk_mul_f32 v[28:29], v[28:29], v[160:161] op_sel_hi:[1,0]
	v_pk_mul_f32 v[26:27], v[26:27], v[160:161] op_sel_hi:[1,0]
	v_pk_mul_f32 v[24:25], v[24:25], v[160:161] op_sel_hi:[1,0]
	v_pk_mul_f32 v[22:23], v[22:23], v[160:161] op_sel_hi:[1,0]
	v_pk_mul_f32 v[20:21], v[20:21], v[160:161] op_sel_hi:[1,0]
	v_pk_mul_f32 v[18:19], v[18:19], v[160:161] op_sel_hi:[1,0]
	v_pk_mul_f32 v[16:17], v[16:17], v[160:161] op_sel_hi:[1,0]
	v_mul_f32_e32 v141, v141, v160
	v_mov_b32_e32 v160, v15
	s_branch .LBB0_866
